# gdn chain step 2: per-row gate values read once with two ds_read_b128 instead of 32 scalar LDS reads; vacuous waits removed
# speedup vs baseline: 1.0271x; 1.0006x over previous
.LBB0_1102:
	s_or_b64 exec, exec, s[0:1]
	v_lshrrev_b32_e32 v91, 4, v68
	v_lshlrev_b32_e32 v89, 2, v91
	v_or_b32_e32 v68, v89, v87
	v_lshl_add_u32 v0, v85, 2, s4
	v_lshl_add_u32 v70, v68, 2, s4
	ds_read_b128 v[184:187], v70
	ds_read_b128 v[188:191], v70 offset:256
	ds_read_b32 v76, v0
	s_waitcnt lgkmcnt(0)
	v_mov_b32_e32 v0, v184
	v_cmp_gt_i32_e32 vcc, v68, v85
	v_sub_f32_e32 v0, v0, v76
	v_min_f32_e32 v0, 0, v0
	v_mul_f32_e32 v0, 0x3fb8aa3b, v0
	v_exp_f32_e32 v71, v0
	s_and_saveexec_b64 s[0:1], vcc
	s_cbranch_execz .LBB0_1104
	v_mov_b32_e32 v0, v188
	v_mul_f32_e32 v0, v62, v0
	v_mul_f32_e32 v69, v71, v0
.LBB0_1104:
	s_or_b64 exec, exec, s[0:1]
	v_lshl_add_u32 v62, v85, 2, 16
	v_lshlrev_b32_e32 v82, 8, v68
	v_add_u32_e32 v72, v62, v82
	ds_write_b32 v72, v69 offset:27648
	v_or_b32_e32 v69, 1, v68
	v_mul_f32_e32 v58, v58, v71
	v_lshl_add_u32 v71, v69, 2, 16
	v_add_u32_e32 v71, 0x11800, v71
	v_mov_b32_e32 v72, v185
	v_lshlrev_b32_e32 v0, 1, v85
	v_sub_u32_e32 v75, v62, v0
	v_cvt_pk_bf16_f32 v58, v58, s0
	v_cmp_ge_i32_e32 vcc, v68, v85
	v_sub_f32_e32 v72, v72, v76
	v_min_f32_e32 v72, 0, v72
	v_mul_f32_e32 v72, 0x3fb8aa3b, v72
	v_exp_f32_e32 v72, v72
	v_mul_lo_u32 v73, v68, s60
	v_cndmask_b32_e32 v58, 0, v58, vcc
	v_add_u32_e32 v77, v75, v73
	ds_write_b16 v77, v58 offset:44032
	v_mov_b32_e32 v58, 0
	v_mov_b32_e32 v93, 0
	s_and_saveexec_b64 s[0:1], vcc
	s_cbranch_execz .LBB0_1106
	v_mov_b32_e32 v92, v189
	v_mul_f32_e32 v63, v63, v92
	v_mul_f32_e32 v93, v72, v63
.LBB0_1106:
	s_or_b64 exec, exec, s[0:1]
	v_mul_f32_e32 v59, v59, v72
	v_cvt_pk_bf16_f32 v59, v59, s0
	v_cmp_ge_i32_e32 vcc, v69, v85
	v_lshlrev_b32_e32 v92, 8, v69
	v_or_b32_e32 v72, 2, v68
	v_cndmask_b32_e32 v59, 0, v59, vcc
	v_add_u32_e32 v63, v62, v92
	ds_write_b16 v77, v59 offset:44176
	v_lshl_add_u32 v59, v72, 2, 16
	ds_write_b32 v63, v93 offset:27648
	v_add_u32_e32 v93, 0x11800, v59
	v_mov_b32_e32 v59, v186
	v_cmp_gt_i32_e32 vcc, v72, v85
	v_sub_f32_e32 v59, v59, v76
	v_min_f32_e32 v59, 0, v59
	v_mul_f32_e32 v59, 0x3fb8aa3b, v59
	v_exp_f32_e32 v59, v59
	s_and_saveexec_b64 s[0:1], vcc
	s_cbranch_execz .LBB0_1108
	v_mov_b32_e32 v58, v190
	v_mul_f32_e32 v58, v64, v58
	v_mul_f32_e32 v58, v59, v58
.LBB0_1108:
	s_or_b64 exec, exec, s[0:1]
	v_lshlrev_b32_e32 v95, 8, v72
	v_add_u32_e32 v63, v62, v95
	ds_write_b32 v63, v58 offset:27648
	v_mul_f32_e32 v58, v60, v59
	v_cvt_pk_bf16_f32 v58, v58, s0
	v_cmp_ge_i32_e32 vcc, v72, v85
	v_or_b32_e32 v94, 3, v68
	v_mov_b32_e32 v60, 0
	v_cndmask_b32_e32 v58, 0, v58, vcc
	ds_write_b16 v77, v58 offset:44320
	v_lshl_add_u32 v58, v94, 2, 16
	v_add_u32_e32 v96, 0x11800, v58
	v_mov_b32_e32 v58, v187
	v_cmp_gt_i32_e32 vcc, v94, v85
	v_sub_f32_e32 v59, v58, v76
	v_min_f32_e32 v59, 0, v59
	v_mul_f32_e32 v59, 0x3fb8aa3b, v59
	v_exp_f32_e32 v59, v59
	v_mov_b32_e32 v58, 0
	s_and_saveexec_b64 s[0:1], vcc
	s_cbranch_execz .LBB0_1110
	v_mov_b32_e32 v60, v191
	v_mul_f32_e32 v60, v65, v60
	v_mul_f32_e32 v60, v59, v60

.LBB0_1112:
	s_or_b64 exec, exec, s[0:1]
	v_lshl_add_u32 v77, v76, 2, 16
	v_add_u32_e32 v77, 0x11800, v77
	ds_read_b32 v77, v77
	v_mov_b32_e32 v98, v184
	v_mov_b32_e32 v99, 0
	v_cmp_gt_i32_e32 vcc, v68, v76
	s_waitcnt lgkmcnt(0)
	v_sub_f32_e32 v98, v98, v77
	v_min_f32_e32 v98, 0, v98
	v_mul_f32_e32 v98, 0x3fb8aa3b, v98
	v_exp_f32_e32 v100, v98
	v_mov_b32_e32 v98, 0
	s_and_saveexec_b64 s[0:1], vcc
	s_cbranch_execz .LBB0_1114
	v_mov_b32_e32 v98, v188
	v_mul_f32_e32 v62, v62, v98
	v_mul_f32_e32 v98, v100, v62
.LBB0_1114:
	s_or_b64 exec, exec, s[0:1]
	v_add_u32_e32 v62, v75, v0
	v_add_u32_e32 v75, v62, v82
	ds_write_b32 v75, v98 offset:27712
	v_mov_b32_e32 v101, v185
	v_mul_f32_e32 v58, v58, v100
	v_sub_u32_e32 v98, 0, v0
	v_add_u32_e32 v75, v62, v98
	v_cvt_pk_bf16_f32 v58, v58, s0
	v_sub_f32_e32 v100, v101, v77
	v_min_f32_e32 v100, 0, v100
	v_mul_f32_e32 v100, 0x3fb8aa3b, v100
	v_exp_f32_e32 v100, v100
	v_cmp_ge_i32_e32 vcc, v68, v76
	s_nop 1
	v_cndmask_b32_e32 v101, 0, v58, vcc
	v_add_u32_e32 v58, v75, v73
	ds_write_b16 v58, v101 offset:44064
	s_and_saveexec_b64 s[0:1], vcc
	s_cbranch_execz .LBB0_1116
	v_mov_b32_e32 v99, v189
	v_mul_f32_e32 v63, v63, v99
	v_mul_f32_e32 v99, v100, v63
.LBB0_1116:
	s_or_b64 exec, exec, s[0:1]
	v_add_u32_e32 v63, v62, v92
	ds_write_b32 v63, v99 offset:27712
	v_mov_b32_e32 v63, v186
	v_mul_f32_e32 v59, v59, v100
	v_cvt_pk_bf16_f32 v59, v59, s0
	v_cmp_ge_i32_e32 vcc, v69, v76
	v_mov_b32_e32 v99, 0
	s_nop 0
	v_cndmask_b32_e32 v59, 0, v59, vcc
	ds_write_b16 v58, v59 offset:44208
	v_sub_f32_e32 v59, v63, v77
	v_min_f32_e32 v59, 0, v59
	v_mul_f32_e32 v59, 0x3fb8aa3b, v59
	v_exp_f32_e32 v63, v59
	v_mov_b32_e32 v59, 0
	v_cmp_gt_i32_e32 vcc, v72, v76
	s_and_saveexec_b64 s[0:1], vcc
	s_cbranch_execz .LBB0_1118
	v_mov_b32_e32 v99, v190
	v_mul_f32_e32 v64, v64, v99
	v_mul_f32_e32 v99, v63, v64
.LBB0_1118:
	s_or_b64 exec, exec, s[0:1]
	v_add_u32_e32 v64, v62, v95
	ds_write_b32 v64, v99 offset:27712
	v_mov_b32_e32 v64, v187
	v_mul_f32_e32 v60, v60, v63
	v_cvt_pk_bf16_f32 v63, v60, s0
	v_cmp_ge_i32_e32 vcc, v72, v76
	v_sub_f32_e32 v60, v64, v77
	v_min_f32_e32 v60, 0, v60
	v_mul_f32_e32 v60, 0x3fb8aa3b, v60
	v_exp_f32_e32 v60, v60
	v_cndmask_b32_e32 v63, 0, v63, vcc
	v_cmp_gt_i32_e32 vcc, v94, v76
	ds_write_b16 v58, v63 offset:44352
	s_and_saveexec_b64 s[0:1], vcc
	s_cbranch_execz .LBB0_1120
	v_mov_b32_e32 v59, v191
	v_mul_f32_e32 v59, v65, v59
	v_mul_f32_e32 v59, v60, v59

.LBB0_1122:
	s_or_b64 exec, exec, s[0:1]
	v_lshl_add_u32 v99, v77, 2, 16
	v_add_u32_e32 v99, 0x11800, v99
	ds_read_b32 v100, v99
	v_mov_b32_e32 v99, v184
	v_cmp_gt_i32_e64 s[0:1], v68, v77
	s_waitcnt lgkmcnt(0)
	v_sub_f32_e32 v99, v99, v100
	v_min_f32_e32 v99, 0, v99
	v_mul_f32_e32 v99, 0x3fb8aa3b, v99
	v_exp_f32_e32 v102, v99
	s_and_saveexec_b64 s[42:43], s[0:1]
	s_cbranch_execz .LBB0_1124
	v_mov_b32_e32 v99, v188
	v_mul_f32_e32 v62, v62, v99
	v_mul_f32_e32 v101, v102, v62
.LBB0_1124:
	s_or_b64 exec, exec, s[42:43]
	v_add_u32_e32 v62, v75, v0
	v_add_u32_e32 v75, v62, v82
	ds_write_b32 v75, v101 offset:27776
	v_mov_b32_e32 v101, v185
	v_mul_f32_e32 v58, v58, v102
	v_add_u32_e32 v99, v62, v98
	v_cvt_pk_bf16_f32 v58, v58, s0
	v_cmp_ge_i32_e64 s[0:1], v68, v77
	v_sub_f32_e32 v101, v101, v100
	v_min_f32_e32 v101, 0, v101
	v_mul_f32_e32 v101, 0x3fb8aa3b, v101
	v_exp_f32_e32 v101, v101
	v_cndmask_b32_e64 v58, 0, v58, s[0:1]
	v_add_u32_e32 v75, v99, v73
	ds_write_b16 v75, v58 offset:44096
	v_mov_b32_e32 v58, 0
	v_mov_b32_e32 v102, 0
	s_and_saveexec_b64 s[42:43], s[0:1]
	s_cbranch_execz .LBB0_1126
	v_mov_b32_e32 v102, v189
	v_mul_f32_e32 v63, v63, v102
	v_mul_f32_e32 v102, v101, v63
.LBB0_1126:
	s_or_b64 exec, exec, s[42:43]
	v_add_u32_e32 v63, v62, v92
	ds_write_b32 v63, v102 offset:27776
	v_mov_b32_e32 v63, v186
	v_mul_f32_e32 v59, v59, v101
	v_cvt_pk_bf16_f32 v101, v59, s0
	v_cmp_ge_i32_e64 s[0:1], v69, v77
	v_sub_f32_e32 v59, v63, v100
	v_min_f32_e32 v59, 0, v59
	v_mul_f32_e32 v59, 0x3fb8aa3b, v59
	v_exp_f32_e32 v59, v59
	v_cndmask_b32_e64 v63, 0, v101, s[0:1]
	v_cmp_gt_i32_e64 s[0:1], v72, v77
	ds_write_b16 v75, v63 offset:44240
	s_and_saveexec_b64 s[42:43], s[0:1]
	s_cbranch_execz .LBB0_1128
	v_mov_b32_e32 v58, v190
	v_mul_f32_e32 v58, v64, v58
	v_mul_f32_e32 v58, v59, v58
.LBB0_1128:
	s_or_b64 exec, exec, s[42:43]
	v_add_u32_e32 v63, v62, v95
	ds_write_b32 v63, v58 offset:27776
	v_mul_f32_e32 v58, v60, v59
	v_mov_b32_e32 v59, v187
	v_cvt_pk_bf16_f32 v58, v58, s0
	v_cmp_ge_i32_e64 s[0:1], v72, v77
	v_mov_b32_e32 v60, 0
	s_nop 0
	v_cndmask_b32_e64 v58, 0, v58, s[0:1]
	ds_write_b16 v75, v58 offset:44384
	v_sub_f32_e32 v58, v59, v100
	v_min_f32_e32 v58, 0, v58
	v_mul_f32_e32 v58, 0x3fb8aa3b, v58
	v_exp_f32_e32 v59, v58
	v_mov_b32_e32 v58, 0
	v_cmp_gt_i32_e64 s[0:1], v94, v77
	s_and_saveexec_b64 s[42:43], s[0:1]
	s_cbranch_execz .LBB0_1130
	v_mov_b32_e32 v60, v191
	v_mul_f32_e32 v60, v65, v60
	v_mul_f32_e32 v60, v59, v60

.LBB0_1132:
	s_or_b64 exec, exec, s[42:43]
	v_lshl_add_u32 v42, v75, 2, 16
	v_add_u32_e32 v42, 0x11800, v42
	ds_read_b32 v42, v42
	v_mov_b32_e32 v43, v184
	v_mov_b32_e32 v45, 0
	v_cmp_gt_i32_e64 s[0:1], v68, v75
	v_mov_b32_e32 v46, 0
	s_waitcnt lgkmcnt(0)
	v_sub_f32_e32 v43, v43, v42
	v_min_f32_e32 v43, 0, v43
	v_mul_f32_e32 v43, 0x3fb8aa3b, v43
	v_exp_f32_e32 v44, v43
	s_and_saveexec_b64 s[42:43], s[0:1]
	s_cbranch_execz .LBB0_1134
	v_mov_b32_e32 v43, v188
	v_mul_f32_e32 v43, v62, v43
	v_mul_f32_e32 v46, v44, v43
.LBB0_1134:
	s_or_b64 exec, exec, s[42:43]
	v_add_u32_e32 v43, v99, v0
	v_add_u32_e32 v47, v43, v82
	ds_write_b32 v47, v46 offset:27840
	v_mov_b32_e32 v46, v185
	v_mul_f32_e32 v44, v58, v44
	v_add_u32_e32 v47, v43, v98
	v_cvt_pk_bf16_f32 v44, v44, s0
	v_cmp_ge_i32_e64 s[0:1], v68, v75
	v_sub_f32_e32 v46, v46, v42
	v_min_f32_e32 v46, 0, v46
	v_mul_f32_e32 v46, 0x3fb8aa3b, v46
	v_exp_f32_e32 v46, v46
	v_cndmask_b32_e64 v48, 0, v44, s[0:1]
	v_add_u32_e32 v44, v47, v73
	ds_write_b16 v44, v48 offset:44128
	s_and_saveexec_b64 s[42:43], s[0:1]
	s_cbranch_execz .LBB0_1136
	v_mov_b32_e32 v45, v189
	v_mul_f32_e32 v45, v63, v45
	v_mul_f32_e32 v45, v46, v45
.LBB0_1136:
	s_or_b64 exec, exec, s[42:43]
	v_add_u32_e32 v47, v43, v92
	ds_write_b32 v47, v45 offset:27840
	v_mul_f32_e32 v45, v59, v46
	v_mov_b32_e32 v46, v186
	v_cvt_pk_bf16_f32 v45, v45, s0
	v_cmp_ge_i32_e64 s[0:1], v69, v75
	v_mov_b32_e32 v47, 0
	s_nop 0
	v_cndmask_b32_e64 v45, 0, v45, s[0:1]
	ds_write_b16 v44, v45 offset:44272
	v_sub_f32_e32 v45, v46, v42
	v_min_f32_e32 v45, 0, v45
	v_mul_f32_e32 v45, 0x3fb8aa3b, v45
	v_exp_f32_e32 v46, v45
	v_mov_b32_e32 v45, 0
	v_cmp_gt_i32_e64 s[0:1], v72, v75
	s_and_saveexec_b64 s[42:43], s[0:1]
	s_cbranch_execz .LBB0_1138
	v_mov_b32_e32 v47, v190
	v_mul_f32_e32 v47, v64, v47
	v_mul_f32_e32 v47, v46, v47
.LBB0_1138:
	s_or_b64 exec, exec, s[42:43]
	v_add_u32_e32 v48, v43, v95
	ds_write_b32 v48, v47 offset:27840
	v_mov_b32_e32 v47, v187
	v_mul_f32_e32 v46, v60, v46
	v_cvt_pk_bf16_f32 v46, v46, s0
	v_cmp_ge_i32_e64 s[0:1], v72, v75
	v_sub_f32_e32 v42, v47, v42
	v_min_f32_e32 v42, 0, v42
	v_mul_f32_e32 v42, 0x3fb8aa3b, v42
	v_exp_f32_e32 v42, v42
	v_cndmask_b32_e64 v46, 0, v46, s[0:1]
	v_cmp_gt_i32_e64 s[0:1], v94, v75
	ds_write_b16 v44, v46 offset:44416
	s_and_saveexec_b64 s[42:43], s[0:1]
	s_cbranch_execz .LBB0_1140
	v_mov_b32_e32 v45, v191
	v_mul_f32_e32 v45, v65, v45
	v_mul_f32_e32 v45, v42, v45
